# ret_state chunk loop: extra look-ahead loads one chunk further (L2 warm-up), counted waits adjusted
# baseline (speedup 1.0000x reference)
; DEVI void ph_ret_state(const int wv, const Params& p, int l, unsigned char* lds_raw) {
;     ...
;         const float e_ = p.in[9][(l * 2 + dir) * 4 + h];
;         const float lg2 = log1pf(-exp2f(-e_)) * 1.4426950408889634f;
;         const float gC = exp2f(128.0f * lg2);
;         f32x4 R[2]; R[0] = (f32x4){0.f, 0.f, 0.f, 0.f}; R[1] = R[0];
;         const int j0 = tid >> 3, g80 = tid & 7;
;         const float wj0 = exp2f((float)(dir == 0 ? 127 - j0 : j0) * lg2), wj1 = exp2f((float)(dir == 0 ? 63 - j0 : j0 + 64) * lg2);
;         u32x4 kwr[2], vwr[2];
;     ...
;         RS_LOAD(0);
;         __syncthreads();
;         RS_WRITE(0);
;         RS_LOAD(1);
.LBB0_542:
	s_bfe_u32 s2, s29, 0x10001
	s_lshl_b32 s0, s2, 2
	s_bfe_u32 s3, s29, 0x20002
	s_or_b32 s0, s0, s28
	s_or_b32 s18, s0, s3
	s_ashr_i32 s37, s29, 4
	s_lshl_b64 s[0:1], s[18:19], 2
	s_add_u32 s0, s78, s0
	s_addc_u32 s1, s79, s1
	global_load_dword v2, v1, s[0:1]
	s_mov_b32 s0, 0x42fc0000
	v_mov_b64_e32 v[14:15], s[24:25]
	s_mov_b32 s5, s19
	s_mov_b32 s7, s19
	v_lshlrev_b32_e32 v0, 1, v18
	v_lshl_add_u32 v57, s37, 11, v46
	v_add_u32_e32 v88, v50, v49
	s_waitcnt vmcnt(0)
	v_cmp_lt_f32_e32 vcc, s0, v2
	s_nop 1
	v_cndmask_b32_e32 v3, 0, v234, vcc
	v_sub_f32_e32 v2, v3, v2
	s_and_b64 s[0:1], vcc, exec
	v_exp_f32_e32 v2, v2
	s_cselect_b32 s0, 0xffffffc0, 0
	s_lshl_b32 s1, s37, 8
	s_lshl_b32 s8, s2, 7
	s_or_b32 s1, s1, s8
	s_add_i32 s1, s1, 0x8000
	v_add_u32_e32 v4, s1, v25
	s_lshl_b32 s6, s29, 6
	s_waitcnt lgkmcnt(0)
	v_ldexp_f32 v24, v2, s0
	v_add_u32_e32 v6, 64, v4
	s_lshl_b32 s4, s3, 7
	s_lshl_b32 s18, s3, 8
	s_and_b32 s36, s6, 64
	s_xor_b32 s9, s1, 0x80
	v_mad_i64_i32 v[2:3], s[0:1], v4, s46, v[14:15]
	v_sub_f32_e32 v26, 1.0, v24
	v_mad_i64_i32 v[16:17], s[0:1], v6, s46, v[14:15]
	s_lshl_b32 s6, s36, 1
	v_lshl_add_u64 v[4:5], v[2:3], 0, s[4:5]
	v_lshl_add_u64 v[2:3], v[2:3], 0, s[18:19]
	v_add_f32_e32 v10, -1.0, v26
	v_frexp_mant_f32_e32 v11, v26
	v_cvt_f64_f32_e32 v[6:7], v26
	s_mov_b32 s0, 0x3f2aaaab
	v_lshl_add_u64 v[2:3], v[2:3], 0, s[6:7]
	v_lshl_add_u64 v[8:9], v[16:17], 0, s[4:5]
	v_sub_f32_e32 v12, v10, v26
	v_frexp_exp_i32_f64_e32 v6, v[6:7]
	v_cmp_gt_f32_e32 vcc, s0, v11
	v_lshl_add_u64 v[4:5], v[4:5], 0, v[0:1]
	v_sub_f32_e64 v27, -v24, v10
	v_lshl_add_u64 v[2:3], v[2:3], 0, v[0:1]
	v_lshl_add_u64 v[22:23], v[8:9], 0, v[0:1]
	v_add_f32_e32 v28, 1.0, v12
	v_subbrev_co_u32_e32 v29, vcc, 0, v6, vcc
	global_load_dwordx4 v[10:13], v[4:5], off
	global_load_dwordx4 v[6:9], v[2:3], off offset:512
	s_nop 0
	global_load_dwordx4 v[2:5], v[22:23], off
	v_add_f32_e32 v23, v27, v28
	v_sub_u32_e32 v27, 0, v29
	v_ldexp_f32 v26, v26, v27
	v_cvt_f32_i32_e32 v22, v29
	v_add_f32_e32 v28, -1.0, v26
	v_add_f32_e32 v29, 1.0, v26
	v_ldexp_f32 v23, v23, v27
	v_add_f32_e32 v27, 1.0, v28
	v_add_f32_e32 v30, -1.0, v29
	v_sub_f32_e32 v27, v26, v27
	v_sub_f32_e32 v26, v26, v30
	v_add_f32_e32 v30, v23, v27
	v_add_f32_e32 v23, v23, v26
	v_add_f32_e32 v32, v29, v23
	v_rcp_f32_e32 v33, v32
	v_add_f32_e32 v27, v28, v30
	v_sub_f32_e32 v28, v27, v28
	v_sub_f32_e32 v26, v32, v29
	v_mul_f32_e32 v35, v27, v33
	v_sub_f32_e32 v34, v30, v28
	v_mul_f32_e32 v28, v32, v35
	v_sub_f32_e32 v23, v23, v26
	v_fma_f32 v30, v35, v32, -v28
	v_fmac_f32_e32 v30, v35, v23
	v_add_f32_e32 v26, v28, v30
	v_sub_f32_e32 v29, v27, v26
	v_mov_b32_e32 v31, v26
	v_pk_add_f32 v[26:27], v[26:27], v[28:29] neg_lo:[0,1] neg_hi:[0,1]
	s_mov_b32 s0, 0x3f317218
	v_pk_add_f32 v[26:27], v[26:27], v[30:31] neg_lo:[0,1] neg_hi:[0,1]
	v_cmp_nlt_f32_e32 vcc, 1.0, v24
	v_add_f32_e32 v27, v34, v27
	v_add_f32_e32 v26, v26, v27
	v_add_f32_e32 v27, v29, v26
	v_mul_f32_e32 v31, v33, v27
	v_mul_f32_e32 v28, v32, v31
	v_sub_f32_e32 v29, v29, v27
	v_add_f32_e32 v36, v35, v31
	v_fma_f32 v30, v31, v32, -v28
	v_add_f32_e32 v34, v26, v29
	v_sub_f32_e32 v26, v36, v35
	v_fmac_f32_e32 v30, v31, v23
	v_sub_f32_e32 v23, v31, v26
	v_add_f32_e32 v26, v28, v30
	v_sub_f32_e32 v29, v27, v26
	v_mov_b32_e32 v31, v26
	v_pk_add_f32 v[26:27], v[26:27], v[28:29] neg_lo:[0,1] neg_hi:[0,1]
	s_lshl_b32 s31, s3, 6
	v_pk_add_f32 v[26:27], v[26:27], v[30:31] neg_lo:[0,1] neg_hi:[0,1]
	v_lshl_add_u64 v[16:17], v[16:17], 0, s[18:19]
	v_add_f32_e32 v27, v34, v27
	v_add_f32_e32 v26, v26, v27
	v_add_f32_e32 v26, v29, v26
	v_mul_f32_e32 v26, v33, v26
	v_add_f32_e32 v23, v23, v26
	v_add_f32_e32 v26, v36, v23
	v_mul_f32_e32 v28, v26, v26
	v_sub_f32_e32 v29, v26, v36
	v_fmamk_f32 v30, v28, 0x3e9b6dac, v224
	v_sub_f32_e32 v29, v23, v29
	v_mul_f32_e32 v23, v26, v28
	v_fmaak_f32 v199, v28, v30, 0x3f2aaada
	v_ldexp_f32 v31, v29, 1
	v_pk_mul_f32 v[28:29], v[22:23], v[198:199]
	v_ldexp_f32 v27, v26, 1
	v_fma_f32 v26, v22, s0, -v28
	v_fmac_f32_e32 v26, 0xb102e308, v22
	v_pk_add_f32 v[22:23], v[28:29], v[26:27]
	v_mov_b32_e32 v30, v28
	v_sub_f32_e32 v34, v23, v27
	v_pk_add_f32 v[32:33], v[22:23], v[28:29] neg_lo:[0,1] neg_hi:[0,1]
	v_sub_f32_e32 v29, v29, v34
	v_add_f32_e32 v31, v31, v29
	v_pk_add_f32 v[36:37], v[22:23], v[30:31]
	v_mov_b32_e32 v27, v22
	v_mov_b32_e32 v33, v37
	v_pk_add_f32 v[38:39], v[26:27], v[32:33] neg_lo:[0,1] neg_hi:[0,1]
	v_pk_add_f32 v[26:27], v[26:27], v[32:33]
	v_mov_b32_e32 v28, v23
	v_mov_b32_e32 v35, v22
	v_pk_add_f32 v[22:23], v[26:27], v[22:23] op_sel:[1,0] op_sel_hi:[0,1] neg_lo:[0,1] neg_hi:[0,1]
	v_mov_b32_e32 v34, v31
	v_mov_b32_e32 v30, v37
	v_mov_b32_e32 v31, v27
	v_mov_b32_e32 v29, v22
	v_pk_add_f32 v[32:33], v[36:37], v[22:23] op_sel_hi:[1,0] neg_lo:[0,1] neg_hi:[0,1]
	v_pk_add_f32 v[22:23], v[30:31], v[28:29] neg_lo:[0,1] neg_hi:[0,1]
	v_mov_b32_e32 v32, v38
	v_pk_add_f32 v[22:23], v[34:35], v[22:23] neg_lo:[0,1] neg_hi:[0,1]
	v_mov_b32_e32 v39, v27
	v_pk_add_f32 v[28:29], v[32:33], v[22:23]
	s_mov_b32 s0, 0x33800000
	v_pk_add_f32 v[30:31], v[28:29], v[28:29] op_sel:[0,1] op_sel_hi:[1,0]
	v_cmp_lt_f32_e64 s[0:1], |v24|, s0
	v_pk_add_f32 v[26:27], v[26:27], v[30:31] op_sel:[1,0] op_sel_hi:[0,1]
	v_mov_b32_e32 v29, v26
	v_mov_b32_e32 v23, v30
	v_pk_add_f32 v[30:31], v[28:29], v[38:39] neg_lo:[0,1] neg_hi:[0,1]
	v_lshl_add_u64 v[16:17], v[16:17], 0, s[6:7]
	v_sub_f32_e32 v27, v28, v30
	v_pk_add_f32 v[22:23], v[22:23], v[30:31] neg_lo:[0,1] neg_hi:[0,1]
	v_sub_f32_e32 v27, v38, v27
	v_add_f32_e32 v22, v22, v27
	v_add_f32_e32 v22, v22, v23
	v_add_f32_e32 v22, v26, v22
	v_cndmask_b32_e32 v22, v235, v22, vcc
	v_cmp_neq_f32_e32 vcc, 1.0, v24
	v_lshl_add_u64 v[16:17], v[16:17], 0, v[0:1]
	global_load_dwordx4 v[26:29], v[16:17], off offset:512
	v_cndmask_b32_e32 v22, v236, v22, vcc
	v_cndmask_b32_e64 v22, v22, -v24, s[0:1]
	v_mul_f32_e32 v86, 0x3fb8aa3b, v22
	v_mul_f32_e32 v22, 0x43000000, v86
	v_cmp_gt_f32_e32 vcc, s39, v22
	s_and_b64 s[0:1], vcc, exec
	s_cselect_b32 s38, 0xffffffc0, 0
	s_lshl_b32 s0, s37, 2
	s_or_b32 s30, s0, s3
	s_mul_i32 s30, s30, 18
	s_or_b32 s0, s30, s2
	s_ashr_i32 s1, s0, 31
	s_lshl_b64 s[12:13], s[0:1], 7
	s_xor_b32 s0, s0, 1
	s_ashr_i32 s1, s0, 31
	s_lshl_b64 s[10:11], s[0:1], 7
	s_cmp_eq_u32 s2, 0
	v_cndmask_b32_e32 v87, 0, v234, vcc
	s_cselect_b64 vcc, -1, 0
	v_cndmask_b32_e32 v22, v25, v42, vcc
	v_cvt_f32_i32_e32 v22, v22
	v_cndmask_b32_e32 v23, v44, v43, vcc
	v_cvt_f32_i32_e32 v23, v23
	v_mul_f32_e32 v24, v86, v22
	v_cmp_gt_f32_e64 s[0:1], s39, v24
	v_mul_f32_e32 v30, v86, v23
	v_cmp_gt_f32_e64 s[2:3], s39, v30
	v_cndmask_b32_e64 v16, 0, v234, s[0:1]
	v_fmac_f32_e32 v16, v86, v22
	v_cndmask_b32_e64 v17, 0, v234, s[2:3]
	v_exp_f32_e32 v16, v16
	v_fmac_f32_e32 v17, v86, v23
	v_exp_f32_e32 v17, v17
	v_cndmask_b32_e64 v22, 0, v237, s[0:1]
	v_ldexp_f32 v55, v16, v22
	v_cndmask_b32_e64 v16, 0, v237, s[2:3]
	v_ldexp_f32 v56, v17, v16
	s_waitcnt vmcnt(3)
; DEVI unsigned cvt_pk_bf16(float lo, float hi) { unsigned r; asm volatile("v_cvt_pk_bf16_f32 %0, %1, %2" : "=v"(r) : "v"(lo), "v"(hi)); return r; }
; DEVI void ph_ret_state(const int wv, const Params& p, int l, unsigned char* lds_raw) {
;     ...
;         RS_LOAD(0);
;         __syncthreads();
;         RS_WRITE(0);
;         RS_LOAD(1);
;         int buf = 0;
;         for (int n = 0; n < 18; ++n) {
;             const int cid = dir == 0 ? n : (n < 2 ? 1 - n : 19 - n);
; #pragma unroll
;             for (int tt = 0; tt < 2; ++tt) { const int t = wave * 2 + tt, dkt = t >> 2, dvt = t & 3;
;                 u32x2 w; w.x = cvt_pk_bf16(R[tt][0], R[tt][1]); w.y = cvt_pk_bf16(R[tt][2], R[tt][3]);
;                 *(u32x2*)(RS + ((size_t)((b * 4 + h) * 18 + cid) * 128 + half * 64 + dvt * 16 + fr) * 128 + dir * 64 + dkt * 16 + 4 * fq) = w; }
;             if (n == 17) break;
;             __syncthreads();
;             if (n + 1 < 17) { RS_WRITE(buf ^ 1); if (n + 2 < 17) RS_LOAD(n + 2); }
	v_lshlrev_b32_e32 v16, 16, v10
	v_and_b32_e32 v10, 0xffff0000, v10
	v_mul_f32_e32 v16, v55, v16
	v_mul_f32_e32 v10, v55, v10
	s_barrier
	v_cvt_pk_bf16_f32 v10, v16, v10
	v_lshlrev_b32_e32 v16, 16, v11
	v_and_b32_e32 v11, 0xffff0000, v11
	v_mul_f32_e32 v16, v55, v16
	v_mul_f32_e32 v11, v55, v11
	v_cvt_pk_bf16_f32 v11, v16, v11
	v_lshlrev_b32_e32 v16, 16, v12
	v_and_b32_e32 v12, 0xffff0000, v12
	v_mul_f32_e32 v16, v55, v16
	v_mul_f32_e32 v12, v55, v12
	v_cvt_pk_bf16_f32 v12, v16, v12
	v_lshlrev_b32_e32 v16, 16, v13
	v_and_b32_e32 v13, 0xffff0000, v13
	v_mul_f32_e32 v13, v55, v13
	v_mul_f32_e32 v16, v55, v16
	v_cvt_pk_bf16_f32 v13, v16, v13
	ds_write_b128 v51, v[10:13]
	s_waitcnt vmcnt(2)
	ds_write_b128 v51, v[6:9] offset:18432
	s_waitcnt vmcnt(1)
	v_lshlrev_b32_e32 v6, 16, v2
	v_and_b32_e32 v2, 0xffff0000, v2
	v_mul_f32_e32 v6, v56, v6
	v_mul_f32_e32 v2, v56, v2
	v_cvt_pk_bf16_f32 v2, v6, v2
	v_lshlrev_b32_e32 v6, 16, v3
	v_and_b32_e32 v3, 0xffff0000, v3
	v_mul_f32_e32 v6, v56, v6
	v_mul_f32_e32 v3, v56, v3
	v_cvt_pk_bf16_f32 v3, v6, v3
	v_lshlrev_b32_e32 v6, 16, v4
	v_and_b32_e32 v4, 0xffff0000, v4
	v_mul_f32_e32 v6, v56, v6
	v_mul_f32_e32 v4, v56, v4
	v_cvt_pk_bf16_f32 v4, v6, v4
	v_lshlrev_b32_e32 v6, 16, v5
	v_and_b32_e32 v5, 0xffff0000, v5
	v_add_u32_e32 v16, s9, v25
	v_mul_f32_e32 v6, v56, v6
	v_mul_f32_e32 v5, v56, v5
	v_mad_i64_i32 v[10:11], s[0:1], v16, s46, v[14:15]
	v_cvt_pk_bf16_f32 v5, v6, v5
	v_lshl_add_u64 v[6:7], v[10:11], 0, s[4:5]
	v_lshl_add_u64 v[6:7], v[6:7], 0, v[0:1]
	global_load_dwordx4 v[6:9], v[6:7], off
	v_add_u32_e32 v16, 64, v16
	v_mad_i64_i32 v[16:17], s[0:1], v16, s46, v[14:15]
	v_lshl_add_u64 v[10:11], v[10:11], 0, s[18:19]
	v_lshl_add_u64 v[22:23], v[16:17], 0, s[4:5]
	v_lshl_add_u64 v[10:11], v[10:11], 0, s[6:7]
	v_lshl_add_u64 v[22:23], v[22:23], 0, v[0:1]
	v_lshl_add_u64 v[10:11], v[10:11], 0, v[0:1]
	global_load_dwordx4 v[30:33], v[22:23], off
	v_lshl_add_u64 v[16:17], v[16:17], 0, s[18:19]
	global_load_dwordx4 v[10:13], v[10:11], off offset:512
	v_lshl_add_u64 v[16:17], v[16:17], 0, s[6:7]
	v_lshl_add_u64 v[16:17], v[16:17], 0, v[0:1]
	global_load_dwordx4 v[34:37], v[16:17], off offset:512
	v_or_b32_e32 v24, s36, v19
	ds_write_b128 v51, v[2:5] offset:9216
	s_waitcnt vmcnt(4)
	ds_write_b128 v51, v[26:29] offset:27648
	v_or_b32_e32 v26, s12, v24
	v_mov_b32_e32 v3, s13
	v_or_b32_e32 v2, s97, v26
	s_mov_b32 s9, s19
	v_lshlrev_b64 v[16:17], 8, v[2:3]
	v_or_b32_e32 v2, s43, v26
	v_lshl_add_u64 v[22:23], v[20:21], 0, s[8:9]
	v_lshlrev_b64 v[2:3], 8, v[2:3]
	v_cvt_pk_bf16_f32 v4, v1, v1
	v_cvt_pk_bf16_f32 v5, v1, v1
	v_lshl_add_u64 v[16:17], v[22:23], 0, v[16:17]
	v_lshl_add_u64 v[2:3], v[22:23], 0, v[2:3]
	global_store_dwordx2 v[16:17], v[4:5], off
	v_cvt_pk_bf16_f32 v4, v1, v1
	v_cvt_pk_bf16_f32 v5, v1, v1
	global_store_dwordx2 v[2:3], v[4:5], off
	s_waitcnt lgkmcnt(0)
	s_barrier
	s_and_b64 s[0:1], vcc, exec
	s_movk_i32 s0, 0x880
	s_cselect_b32 s0, 0x100, s0
	v_fmac_f32_e32 v87, 0x43000000, v86
	s_mov_b32 s8, 0
	s_waitcnt vmcnt(5)
	v_lshlrev_b32_e32 v2, 16, v6
	v_and_b32_e32 v3, 0xffff0000, v6
	v_mul_f32_e32 v2, v55, v2
	v_mul_f32_e32 v3, v55, v3
	v_cvt_pk_bf16_f32 v2, v2, v3
	v_lshlrev_b32_e32 v3, 16, v7
	v_and_b32_e32 v4, 0xffff0000, v7
	v_mul_f32_e32 v3, v55, v3
	v_mul_f32_e32 v4, v55, v4
	v_cvt_pk_bf16_f32 v3, v3, v4
	v_lshlrev_b32_e32 v4, 16, v8
	v_and_b32_e32 v5, 0xffff0000, v8
	v_mul_f32_e32 v4, v55, v4
	v_mul_f32_e32 v5, v55, v5
	v_cvt_pk_bf16_f32 v4, v4, v5
	v_lshlrev_b32_e32 v5, 16, v9
	v_mul_f32_e32 v5, v55, v5
	v_and_b32_e32 v6, 0xffff0000, v9
	v_mul_f32_e32 v6, v55, v6
	v_cvt_pk_bf16_f32 v5, v5, v6
	ds_write_b128 v51, v[2:5] offset:36864
	s_waitcnt vmcnt(3)
	ds_write_b128 v51, v[10:13] offset:55296
	v_lshlrev_b32_e32 v2, 16, v30
	v_and_b32_e32 v3, 0xffff0000, v30
	v_mul_f32_e32 v2, v56, v2
	v_mul_f32_e32 v3, v56, v3
	v_cvt_pk_bf16_f32 v2, v2, v3
	v_lshlrev_b32_e32 v3, 16, v31
	v_and_b32_e32 v4, 0xffff0000, v31
	v_mul_f32_e32 v3, v56, v3
	v_mul_f32_e32 v4, v56, v4
	v_cvt_pk_bf16_f32 v3, v3, v4
	v_lshlrev_b32_e32 v4, 16, v32
	v_and_b32_e32 v5, 0xffff0000, v32
	v_mul_f32_e32 v4, v56, v4
	v_mul_f32_e32 v5, v56, v5
	v_cvt_pk_bf16_f32 v4, v4, v5
	v_lshlrev_b32_e32 v5, 16, v33
	v_mul_f32_e32 v5, v56, v5
	v_and_b32_e32 v6, 0xffff0000, v33
	v_mul_f32_e32 v6, v56, v6
	v_cvt_pk_bf16_f32 v5, v5, v6
	v_add_u32_e32 v10, s0, v57
	ds_write_b128 v51, v[2:5] offset:46080
	s_waitcnt vmcnt(2)
	ds_write_b128 v51, v[34:37] offset:64512
	v_mad_i64_i32 v[2:3], s[0:1], v10, s46, v[14:15]
	v_lshl_add_u64 v[4:5], v[2:3], 0, s[4:5]
	v_lshl_add_u64 v[2:3], v[2:3], 0, s[18:19]
	v_lshl_add_u64 v[2:3], v[2:3], 0, s[6:7]
	v_lshl_add_u64 v[4:5], v[4:5], 0, v[0:1]
	v_lshl_add_u64 v[6:7], v[2:3], 0, v[0:1]
	global_load_dwordx4 v[2:5], v[4:5], off
	s_nop 0
	global_load_dwordx4 v[6:9], v[6:7], off offset:512
	v_add_u32_e32 v10, 64, v10
	v_mad_i64_i32 v[16:17], s[0:1], v10, s46, v[14:15]
	v_lshl_add_u64 v[10:11], v[16:17], 0, s[4:5]
	v_lshl_add_u64 v[10:11], v[10:11], 0, v[0:1]
	global_load_dwordx4 v[10:13], v[10:11], off
	ds_read_b64_tr_b16 v[26:27], v88 offset:18432
	ds_read_b64_tr_b16 v[30:31], v52
	ds_read_b64_tr_b16 v[32:33], v52 offset:576
	ds_read_b64_tr_b16 v[34:35], v52 offset:4608
	ds_read_b64_tr_b16 v[36:37], v52 offset:5184
	ds_read_b64_tr_b16 v[28:29], v88 offset:19008
	ds_read_b64_tr_b16 v[38:39], v88 offset:23040
	ds_read_b64_tr_b16 v[58:59], v88 offset:23072
	ds_read_b64_tr_b16 v[64:65], v88 offset:19040
	ds_read_b64_tr_b16 v[62:63], v88 offset:18464
	ds_read_b64_tr_b16 v[68:69], v88 offset:32864
	s_waitcnt lgkmcnt(5)
; #define LAS __attribute__((address_space(3)))
; DEVI unsigned cvt_pk_bf16(float lo, float hi) { unsigned r; asm volatile("v_cvt_pk_bf16_f32 %0, %1, %2" : "=v"(r) : "v"(lo), "v"(hi)); return r; }
; #define MFMA16(X, Y, ACC) __builtin_amdgcn_mfma_f32_16x16x32_bf16((X), (Y), (ACC), 0, 0, 0)
; DEVI void ph_ret_state(const int wv, const Params& p, int l, unsigned char* lds_raw) {
;     ...
;         for (int n = 0; n < 18; ++n) {
;             const int cid = dir == 0 ? n : (n < 2 ? 1 - n : 19 - n);
; #pragma unroll
;             for (int tt = 0; tt < 2; ++tt) { const int t = wave * 2 + tt, dkt = t >> 2, dvt = t & 3;
;                 u32x2 w; w.x = cvt_pk_bf16(R[tt][0], R[tt][1]); w.y = cvt_pk_bf16(R[tt][2], R[tt][3]);
;                 *(u32x2*)(RS + ((size_t)((b * 4 + h) * 18 + cid) * 128 + half * 64 + dvt * 16 + fr) * 128 + dir * 64 + dkt * 16 + 4 * fq) = w; }
;             if (n == 17) break;
;             __syncthreads();
;             if (n + 1 < 17) { RS_WRITE(buf ^ 1); if (n + 2 < 17) RS_LOAD(n + 2); }
;             LAS unsigned char* Kb = Kt + buf * 36864; LAS unsigned char* Vb = Kb + 18432;
; #pragma unroll
;             for (int tt = 0; tt < 2; ++tt) { const int t = wave * 2 + tt, dkt = t >> 2, dvt = t & 3;
;                 f32x4 u = (f32x4){0.f, 0.f, 0.f, 0.f};
; #pragma unroll
;                 for (int ks = 0; ks < 4; ++ks) { const bf16x8 xf = tr_frag(Kb, 144, ks * 32 + 8 * fq, ks * 32 + 8 * fq + 4, dkt * 16, fr), yf = tr_frag(Vb, 144, ks * 32 + 8 * fq, ks * 32 + 8 * fq + 4, dvt * 16, fr); u = MFMA16(xf, yf, u); }
;                 R[tt] = R[tt] * gC + u; }
	v_mfma_f32_16x16x32_bf16 v[26:29], v[30:33], v[26:29], 0
	ds_read_b64_tr_b16 v[40:41], v88 offset:23616
	ds_read_b64_tr_b16 v[70:71], v52 offset:9216
	ds_read_b64_tr_b16 v[72:73], v52 offset:9792
	ds_read_b64_tr_b16 v[74:75], v88 offset:27648
	ds_read_b64_tr_b16 v[78:79], v88 offset:27680
	ds_read_b64_tr_b16 v[60:61], v88 offset:23648
	v_lshl_add_u64 v[16:17], v[16:17], 0, s[18:19]
	v_lshl_add_u64 v[16:17], v[16:17], 0, s[6:7]
	s_waitcnt lgkmcnt(5)
	v_mfma_f32_16x16x32_bf16 v[26:29], v[34:37], v[38:41], v[26:29]
	ds_read_b64_tr_b16 v[76:77], v88 offset:28224
	ds_read_b64_tr_b16 v[38:39], v52 offset:13824
	ds_read_b64_tr_b16 v[40:41], v52 offset:14400
	ds_read_b64_tr_b16 v[82:83], v88 offset:32256
	ds_read_b64_tr_b16 v[66:67], v88 offset:32288
	ds_read_b64_tr_b16 v[80:81], v88 offset:28256
	ds_read_b64_tr_b16 v[84:85], v88 offset:32832
	v_lshl_add_u64 v[16:17], v[16:17], 0, v[0:1]
	s_waitcnt lgkmcnt(6)
	v_mfma_f32_16x16x32_bf16 v[26:29], v[70:73], v[74:77], v[26:29]
	s_movk_i32 s0, 0x800
	s_cselect_b32 s0, 0x180, s0
	s_lshl_b32 s2, s36, 1
	s_waitcnt lgkmcnt(0)
	v_mfma_f32_16x16x32_bf16 v[74:77], v[38:41], v[82:85], v[26:29]
	v_mfma_f32_16x16x32_bf16 v[26:29], v[30:33], v[62:65], 0
	global_load_dwordx4 v[62:65], v[16:17], off offset:512
	v_exp_f32_e32 v16, v87
	v_mov_b32_e32 v17, s11
	v_mfma_f32_16x16x32_bf16 v[26:29], v[34:37], v[58:61], v[26:29]
	v_mfma_f32_16x16x32_bf16 v[34:37], v[70:73], v[78:81], v[26:29]
	v_mfma_f32_16x16x32_bf16 v[34:37], v[38:41], v[66:69], v[34:37]
	s_nop 5
	v_ldexp_f32 v26, v16, s38
	v_pk_fma_f32 v[30:31], v[26:27], 0, v[76:77] op_sel_hi:[0,0,1]
	v_pk_fma_f32 v[32:33], v[26:27], 0, v[74:75] op_sel_hi:[0,0,1]
	v_cvt_pk_bf16_f32 v28, v32, v33
	v_cvt_pk_bf16_f32 v29, v30, v31
	v_pk_fma_f32 v[38:39], v[26:27], 0, v[36:37] op_sel_hi:[0,0,1]
	v_pk_fma_f32 v[40:41], v[26:27], 0, v[34:35] op_sel_hi:[0,0,1]
	v_or_b32_e32 v27, s10, v24
	v_or_b32_e32 v16, s97, v27
	v_lshlrev_b64 v[34:35], 8, v[16:17]
	v_or_b32_e32 v16, s43, v27
	v_lshlrev_b64 v[16:17], 8, v[16:17]
	v_lshl_add_u64 v[34:35], v[22:23], 0, v[34:35]
	v_lshl_add_u64 v[16:17], v[22:23], 0, v[16:17]
	global_store_dwordx2 v[34:35], v[28:29], off
	v_cvt_pk_bf16_f32 v28, v40, v41
	v_cvt_pk_bf16_f32 v29, v38, v39
	global_store_dwordx2 v[16:17], v[28:29], off
	s_barrier
	s_waitcnt vmcnt(5)
	v_lshlrev_b32_e32 v16, 16, v2
	v_and_b32_e32 v2, 0xffff0000, v2
	v_mul_f32_e32 v16, v55, v16
	v_mul_f32_e32 v2, v55, v2
	v_cvt_pk_bf16_f32 v2, v16, v2
	v_lshlrev_b32_e32 v16, 16, v3
	v_and_b32_e32 v3, 0xffff0000, v3
	v_mul_f32_e32 v16, v55, v16
	v_mul_f32_e32 v3, v55, v3
	v_cvt_pk_bf16_f32 v3, v16, v3
	v_lshlrev_b32_e32 v16, 16, v4
	v_and_b32_e32 v4, 0xffff0000, v4
	v_mul_f32_e32 v16, v55, v16
	v_mul_f32_e32 v4, v55, v4
	v_cvt_pk_bf16_f32 v4, v16, v4
	v_lshlrev_b32_e32 v16, 16, v5
	v_and_b32_e32 v5, 0xffff0000, v5
	v_mul_f32_e32 v5, v55, v5
	v_mul_f32_e32 v16, v55, v16
	v_cvt_pk_bf16_f32 v5, v16, v5
	ds_write_b128 v51, v[2:5]
	s_waitcnt vmcnt(4)
	ds_write_b128 v51, v[6:9] offset:18432
	s_waitcnt vmcnt(3)
	v_lshlrev_b32_e32 v2, 16, v10
	v_and_b32_e32 v3, 0xffff0000, v10
	v_mul_f32_e32 v2, v56, v2
	v_mul_f32_e32 v3, v56, v3
	v_cvt_pk_bf16_f32 v2, v2, v3
	v_lshlrev_b32_e32 v3, 16, v11
	v_and_b32_e32 v4, 0xffff0000, v11
	v_mul_f32_e32 v3, v56, v3
	v_mul_f32_e32 v4, v56, v4
	v_cvt_pk_bf16_f32 v3, v3, v4
	v_lshlrev_b32_e32 v4, 16, v12
	v_and_b32_e32 v5, 0xffff0000, v12
	v_mul_f32_e32 v4, v56, v4
	v_mul_f32_e32 v5, v56, v5
	v_cvt_pk_bf16_f32 v4, v4, v5
	v_lshlrev_b32_e32 v5, 16, v13
	v_mul_f32_e32 v5, v56, v5
	v_and_b32_e32 v6, 0xffff0000, v13
	v_mul_f32_e32 v6, v56, v6
	v_cvt_pk_bf16_f32 v5, v5, v6
	v_add_u32_e32 v10, s0, v57
	ds_write_b128 v51, v[2:5] offset:9216
	s_waitcnt vmcnt(2)
	ds_write_b128 v51, v[62:65] offset:27648
	v_mad_i64_i32 v[2:3], s[0:1], v10, s46, v[14:15]
	v_lshl_add_u64 v[4:5], v[2:3], 0, s[4:5]
	v_lshl_add_u64 v[2:3], v[2:3], 0, s[18:19]
	v_lshl_add_u64 v[2:3], v[2:3], 0, s[6:7]
	v_lshl_add_u64 v[4:5], v[4:5], 0, v[0:1]
	v_lshl_add_u64 v[6:7], v[2:3], 0, v[0:1]
	v_add_u32_e32 v10, 64, v10
	global_load_dwordx4 v[2:5], v[4:5], off
	s_nop 0
	global_load_dwordx4 v[6:9], v[6:7], off offset:512
	v_mad_i64_i32 v[28:29], s[0:1], v10, s46, v[14:15]
	ds_read_b64_tr_b16 v[10:11], v52 offset:36864
	ds_read_b64_tr_b16 v[12:13], v52 offset:37440
	ds_read_b64_tr_b16 v[34:35], v52 offset:41472
	ds_read_b64_tr_b16 v[36:37], v52 offset:42048
	ds_read_b64_tr_b16 v[16:17], v88 offset:55872
	ds_read_b64_tr_b16 v[14:15], v88 offset:55296
	ds_read_b64_tr_b16 v[60:61], v88 offset:55904
	ds_read_b64_tr_b16 v[58:59], v88 offset:55328
	ds_read_b64_tr_b16 v[62:63], v88 offset:59904
	ds_read_b64_tr_b16 v[64:65], v88 offset:60480
	s_waitcnt lgkmcnt(4)
	v_mfma_f32_16x16x32_bf16 v[14:17], v[10:13], v[14:17], 0
	ds_read_b64_tr_b16 v[68:69], v88 offset:60512
	ds_read_b64_tr_b16 v[66:67], v88 offset:59936
	v_lshl_add_u64 v[86:87], v[28:29], 0, s[4:5]
	v_lshl_add_u64 v[86:87], v[86:87], 0, v[0:1]
	s_waitcnt lgkmcnt(2)
	v_mfma_f32_16x16x32_bf16 v[14:17], v[34:37], v[62:65], v[14:17]
	ds_read_b64_tr_b16 v[62:63], v52 offset:46080
	ds_read_b64_tr_b16 v[64:65], v52 offset:46656
	ds_read_b64_tr_b16 v[70:71], v88 offset:64512
	ds_read_b64_tr_b16 v[72:73], v88 offset:65088
	ds_read_b64_tr_b16 v[74:75], v52 offset:50688
	ds_read_b64_tr_b16 v[76:77], v52 offset:51264
	ds_read_b64_tr_b16 v[80:81], v54 offset:55296
	ds_read_b64_tr_b16 v[78:79], v53 offset:55296
	ds_read_b64_tr_b16 v[84:85], v88 offset:65120
	ds_read_b64_tr_b16 v[82:83], v88 offset:64544
	s_mov_b32 s5, 4
	s_lshl_b32 s0, s4, 1
	s_waitcnt lgkmcnt(6)
	v_mfma_f32_16x16x32_bf16 v[14:17], v[62:65], v[70:73], v[14:17]
	ds_read_b64_tr_b16 v[72:73], v54 offset:55328
	ds_read_b64_tr_b16 v[70:71], v53 offset:55328
	s_waitcnt lgkmcnt(4)
	v_mfma_f32_16x16x32_bf16 v[78:81], v[74:77], v[78:81], v[14:17]
	s_nop 3
	v_lshl_add_u64 v[14:15], v[28:29], 0, s[18:19]
	v_lshl_add_u64 v[14:15], v[14:15], 0, s[6:7]
	v_lshl_add_u64 v[14:15], v[14:15], 0, v[0:1]
	v_mfma_f32_16x16x32_bf16 v[58:61], v[10:13], v[58:61], 0
	global_load_dwordx4 v[10:13], v[86:87], off
	s_nop 0
	global_load_dwordx4 v[14:17], v[14:15], off offset:512
	global_load_dwordx4 v[140:143], v1, s[24:25]
	global_load_dwordx4 v[144:147], v1, s[24:25]
	global_load_dwordx4 v[148:151], v1, s[24:25]
	global_load_dwordx4 v[152:155], v1, s[24:25]
	v_mov_b32_e32 v28, v26
	v_mov_b32_e32 v29, v26
	v_mfma_f32_16x16x32_bf16 v[34:37], v[34:37], v[66:69], v[58:61]
	s_mov_b32 s6, 17
	s_lshl_b32 s18, s31, 1
	s_waitcnt lgkmcnt(2)
	v_mfma_f32_16x16x32_bf16 v[58:61], v[62:65], v[82:85], v[34:37]
	s_nop 3
	v_fma_f32 v36, v26, v30, v80
	v_fma_f32 v37, v26, v31, v81
	v_pk_fma_f32 v[34:35], v[26:27], v[32:33], v[78:79] op_sel_hi:[0,1,1]
	s_waitcnt lgkmcnt(0)
	v_mfma_f32_16x16x32_bf16 v[30:33], v[74:77], v[70:73], v[58:61]
	s_nop 7
	v_pk_fma_f32 v[32:33], v[26:27], v[38:39], v[32:33] op_sel_hi:[0,1,1]
	v_pk_fma_f32 v[30:31], v[26:27], v[40:41], v[30:31] op_sel_hi:[0,1,1]
; DEVI unsigned cvt_pk_bf16(float lo, float hi) { unsigned r; asm volatile("v_cvt_pk_bf16_f32 %0, %1, %2" : "=v"(r) : "v"(lo), "v"(hi)); return r; }
; DEVI void ph_ret_state(const int wv, const Params& p, int l, unsigned char* lds_raw) {
;     ...
;         RS_LOAD(0);
;         __syncthreads();
;         RS_WRITE(0);
;         RS_LOAD(1);
;         int buf = 0;
;         for (int n = 0; n < 18; ++n) {
;             const int cid = dir == 0 ? n : (n < 2 ? 1 - n : 19 - n);
; #pragma unroll
;             for (int tt = 0; tt < 2; ++tt) { const int t = wave * 2 + tt, dkt = t >> 2, dvt = t & 3;
;                 u32x2 w; w.x = cvt_pk_bf16(R[tt][0], R[tt][1]); w.y = cvt_pk_bf16(R[tt][2], R[tt][3]);
;                 *(u32x2*)(RS + ((size_t)((b * 4 + h) * 18 + cid) * 128 + half * 64 + dvt * 16 + fr) * 128 + dir * 64 + dkt * 16 + 4 * fq) = w; }
;             if (n == 17) break;
;             __syncthreads();
;             if (n + 1 < 17) { RS_WRITE(buf ^ 1); if (n + 2 < 17) RS_LOAD(n + 2); }
.LBB0_543:
	s_add_i32 s1, s5, -2
	s_and_b64 s[10:11], vcc, exec
	s_cselect_b32 s3, s1, s6
	s_add_i32 s10, s3, s30
	s_ashr_i32 s11, s10, 31
	s_lshl_b64 s[10:11], s[10:11], 7
	v_or_b32_e32 v27, s10, v24
	v_mov_b32_e32 v41, s11
	v_or_b32_e32 v40, s97, v27
	v_lshlrev_b64 v[58:59], 8, v[40:41]
	v_or_b32_e32 v40, s43, v27
	v_cvt_pk_bf16_f32 v38, v34, v35
	v_lshl_add_u64 v[58:59], v[22:23], 0, v[58:59]
	v_lshlrev_b64 v[40:41], 8, v[40:41]
	v_cvt_pk_bf16_f32 v39, v36, v37
	global_store_dwordx2 v[58:59], v[38:39], off
	v_cvt_pk_bf16_f32 v38, v30, v31
	v_lshl_add_u64 v[40:41], v[22:23], 0, v[40:41]
	v_cvt_pk_bf16_f32 v39, v32, v33
	global_store_dwordx2 v[40:41], v[38:39], off
	s_waitcnt vmcnt(9)
	v_lshlrev_b32_e32 v27, 16, v2
	v_and_b32_e32 v38, 0xffff0000, v2
	v_mul_f32_e32 v27, v55, v27
	v_mul_f32_e32 v38, v55, v38
	s_barrier
	v_cvt_pk_bf16_f32 v38, v27, v38
	v_lshlrev_b32_e32 v27, 16, v3
	v_and_b32_e32 v39, 0xffff0000, v3
	v_mul_f32_e32 v27, v55, v27
	v_mul_f32_e32 v39, v55, v39
	v_cvt_pk_bf16_f32 v39, v27, v39
	v_lshlrev_b32_e32 v27, 16, v4
	v_and_b32_e32 v40, 0xffff0000, v4
	s_xor_b32 s7, s8, 1
	v_mul_f32_e32 v27, v55, v27
	v_mul_f32_e32 v40, v55, v40
	s_mul_i32 s3, s7, 0x9000
	v_cvt_pk_bf16_f32 v40, v27, v40
	v_lshlrev_b32_e32 v27, 16, v5
	v_and_b32_e32 v41, 0xffff0000, v5
	s_add_i32 s4, s3, 0
	v_mul_f32_e32 v27, v55, v27
	v_mul_f32_e32 v41, v55, v41
	v_cvt_pk_bf16_f32 v41, v27, v41
	v_add3_u32 v27, s4, v45, v48
	ds_write_b128 v27, v[38:41]
	s_waitcnt vmcnt(8)
	ds_write_b128 v27, v[6:9] offset:18432
	s_waitcnt vmcnt(7)
	v_lshlrev_b32_e32 v38, 16, v10
	v_and_b32_e32 v39, 0xffff0000, v10
	v_mul_f32_e32 v38, v56, v38
	v_mul_f32_e32 v39, v56, v39
	v_cvt_pk_bf16_f32 v38, v38, v39
	v_lshlrev_b32_e32 v39, 16, v11
	v_and_b32_e32 v40, 0xffff0000, v11
	v_mul_f32_e32 v39, v56, v39
	v_mul_f32_e32 v40, v56, v40
	v_cvt_pk_bf16_f32 v39, v39, v40
	v_lshlrev_b32_e32 v40, 16, v12
	v_and_b32_e32 v41, 0xffff0000, v12
	v_mul_f32_e32 v40, v56, v40
	v_mul_f32_e32 v41, v56, v41
	v_cvt_pk_bf16_f32 v40, v40, v41
	v_lshlrev_b32_e32 v41, 16, v13
	v_mul_f32_e32 v41, v56, v41
	v_and_b32_e32 v58, 0xffff0000, v13
	s_cmp_gt_u32 s1, 14
	v_mul_f32_e32 v58, v56, v58
	v_cvt_pk_bf16_f32 v41, v41, v58
	ds_write_b128 v27, v[38:41] offset:9216
	s_waitcnt vmcnt(6)
	ds_write_b128 v27, v[14:17] offset:27648
	s_cbranch_scc1 .LBB0_545
	s_add_i32 s1, s6, -2
	s_and_b64 s[10:11], vcc, exec
	s_cselect_b32 s1, s5, s1
	s_mov_b32 s60, 0xfff50000
	s_cselect_b32 s60, 0xb0000, s60
	s_cselect_b32 s61, 0, -1
	v_lshl_add_u32 v12, s1, 7, v57
	v_mov_b64_e32 v[10:11], s[24:25]
	v_mad_i64_i32 v[2:3], s[10:11], v12, s46, v[10:11]
	v_add_u32_e32 v12, 64, v12
	s_mov_b32 s1, s19
	v_mad_i64_i32 v[10:11], s[10:11], v12, s46, v[10:11]
	v_lshl_add_u64 v[4:5], v[2:3], 0, s[18:19]
	v_lshl_add_u64 v[2:3], v[2:3], 0, s[0:1]
	s_mov_b32 s3, s19
	v_lshl_add_u64 v[12:13], v[10:11], 0, s[18:19]
	v_lshl_add_u64 v[10:11], v[10:11], 0, s[0:1]
	v_lshl_add_u64 v[2:3], v[2:3], 0, s[2:3]
	v_lshl_add_u64 v[10:11], v[10:11], 0, s[2:3]
	v_lshl_add_u64 v[4:5], v[4:5], 0, v[0:1]
	v_lshl_add_u64 v[6:7], v[2:3], 0, v[0:1]
	v_lshl_add_u64 v[12:13], v[12:13], 0, v[0:1]
	v_lshl_add_u64 v[14:15], v[10:11], 0, v[0:1]
	v_lshl_add_u64 v[156:157], v[4:5], 0, s[60:61]
	v_lshl_add_u64 v[158:159], v[6:7], 0, s[60:61]
	v_lshl_add_u64 v[160:161], v[12:13], 0, s[60:61]
	v_lshl_add_u64 v[162:163], v[14:15], 0, s[60:61]
	global_load_dwordx4 v[2:5], v[4:5], off
	s_nop 0
	global_load_dwordx4 v[6:9], v[6:7], off offset:512
	s_nop 0
	global_load_dwordx4 v[10:13], v[12:13], off
	s_nop 0
	global_load_dwordx4 v[14:17], v[14:15], off offset:512
	global_load_dwordx4 v[140:143], v[156:157], off
	global_load_dwordx4 v[144:147], v[158:159], off offset:512
	global_load_dwordx4 v[148:151], v[160:161], off
	global_load_dwordx4 v[152:155], v[162:163], off offset:512
